# GEMM loops: static priority raise moved to the leading half-workgroup (waves 0-3) instead of the trailing half
# speedup vs baseline: 1.0035x; 1.0003x over previous
.LBB0_191:
	s_ashr_i32 s9, s8, 31
	s_lshl_b64 s[10:11], s[8:9], 20
	s_add_u32 s10, s66, s10
	s_addc_u32 s11, s67, s11
	s_and_b64 s[12:13], s[0:1], exec
	s_cselect_b32 s9, s11, s15
	s_cselect_b32 s30, s10, s14
	s_ashr_i32 s7, s6, 31
	s_lshl_b64 s[12:13], s[6:7], 20
	s_add_u32 s12, s50, s12
	s_addc_u32 s13, s51, s13
	s_and_b64 s[18:19], s[0:1], exec
	s_cselect_b32 s7, s13, s17
	s_cselect_b32 s31, s12, s16
	s_add_u32 s33, s16, 0x100
	s_addc_u32 s34, s17, 0
	s_add_u32 s14, s14, 0x80080
	v_mov_b32_e32 v0, 0
	s_addc_u32 s15, s15, 0
	s_mov_b32 s35, -2
	v_mov_b32_e32 v1, v0
	v_mov_b32_e32 v2, v0
	v_mov_b32_e32 v3, v0
	v_mov_b32_e32 v4, v0
	v_mov_b32_e32 v5, v0
	v_mov_b32_e32 v6, v0
	v_mov_b32_e32 v7, v0
	v_mov_b32_e32 v8, v0
	v_mov_b32_e32 v9, v0
	v_mov_b32_e32 v10, v0
	v_mov_b32_e32 v11, v0
	v_mov_b32_e32 v16, v0
	v_mov_b32_e32 v17, v0
	v_mov_b32_e32 v18, v0
	v_mov_b32_e32 v19, v0
	v_mov_b32_e32 v24, v0
	v_mov_b32_e32 v25, v0
	v_mov_b32_e32 v26, v0
	v_mov_b32_e32 v27, v0
	v_mov_b32_e32 v32, v0
	v_mov_b32_e32 v33, v0
	v_mov_b32_e32 v34, v0
	v_mov_b32_e32 v35, v0
	v_mov_b32_e32 v40, v0
	v_mov_b32_e32 v41, v0
	v_mov_b32_e32 v42, v0
	v_mov_b32_e32 v43, v0
	v_mov_b32_e32 v48, v0
	v_mov_b32_e32 v49, v0
	v_mov_b32_e32 v50, v0
	v_mov_b32_e32 v51, v0
	v_mov_b32_e32 v12, v0
	v_mov_b32_e32 v13, v0
	v_mov_b32_e32 v14, v0
	v_mov_b32_e32 v15, v0
	v_mov_b32_e32 v20, v0
	v_mov_b32_e32 v21, v0
	v_mov_b32_e32 v22, v0
	v_mov_b32_e32 v23, v0
	v_mov_b32_e32 v28, v0
	v_mov_b32_e32 v29, v0
	v_mov_b32_e32 v30, v0
	v_mov_b32_e32 v31, v0
	v_mov_b32_e32 v36, v0
	v_mov_b32_e32 v37, v0
	v_mov_b32_e32 v38, v0
	v_mov_b32_e32 v39, v0
	v_mov_b32_e32 v44, v0
	v_mov_b32_e32 v45, v0
	v_mov_b32_e32 v46, v0
	v_mov_b32_e32 v47, v0
	v_mov_b32_e32 v52, v0
	v_mov_b32_e32 v53, v0
	v_mov_b32_e32 v54, v0
	v_mov_b32_e32 v55, v0
	v_mov_b32_e32 v56, v0
	v_mov_b32_e32 v57, v0
	v_mov_b32_e32 v58, v0
	v_mov_b32_e32 v59, v0
	v_mov_b32_e32 v60, v0
	v_mov_b32_e32 v61, v0
	v_mov_b32_e32 v62, v0
	v_mov_b32_e32 v63, v0
	v_mov_b32_e32 v64, v0
	v_mov_b32_e32 v65, v0
	v_mov_b32_e32 v66, v0
	v_mov_b32_e32 v67, v0
	v_mov_b32_e32 v68, v0
	v_mov_b32_e32 v69, v0
	v_mov_b32_e32 v70, v0
	v_mov_b32_e32 v71, v0
	v_mov_b32_e32 v72, v0
	v_mov_b32_e32 v73, v0
	v_mov_b32_e32 v74, v0
	v_mov_b32_e32 v75, v0
	v_mov_b32_e32 v80, v0
	v_mov_b32_e32 v81, v0
	v_mov_b32_e32 v82, v0
	v_mov_b32_e32 v83, v0
	v_mov_b32_e32 v88, v0
	v_mov_b32_e32 v89, v0
	v_mov_b32_e32 v90, v0
	v_mov_b32_e32 v91, v0
	v_mov_b32_e32 v96, v0
	v_mov_b32_e32 v97, v0
	v_mov_b32_e32 v98, v0
	v_mov_b32_e32 v99, v0
	v_mov_b32_e32 v104, v0
	v_mov_b32_e32 v105, v0
	v_mov_b32_e32 v106, v0
	v_mov_b32_e32 v107, v0
	v_mov_b32_e32 v112, v0
	v_mov_b32_e32 v113, v0
	v_mov_b32_e32 v114, v0
	v_mov_b32_e32 v115, v0
	v_mov_b32_e32 v76, v0
	v_mov_b32_e32 v77, v0
	v_mov_b32_e32 v78, v0
	v_mov_b32_e32 v79, v0
	v_mov_b32_e32 v84, v0
	v_mov_b32_e32 v85, v0
	v_mov_b32_e32 v86, v0
	v_mov_b32_e32 v87, v0
	v_mov_b32_e32 v92, v0
	v_mov_b32_e32 v93, v0
	v_mov_b32_e32 v94, v0
	v_mov_b32_e32 v95, v0
	v_mov_b32_e32 v100, v0
	v_mov_b32_e32 v101, v0
	v_mov_b32_e32 v102, v0
	v_mov_b32_e32 v103, v0
	v_mov_b32_e32 v108, v0
	v_mov_b32_e32 v109, v0
	v_mov_b32_e32 v110, v0
	v_mov_b32_e32 v111, v0
	v_mov_b32_e32 v116, v0
	v_mov_b32_e32 v117, v0
	v_mov_b32_e32 v118, v0
	v_mov_b32_e32 v119, v0
	v_mov_b32_e32 v120, v0
	v_mov_b32_e32 v121, v0
	v_mov_b32_e32 v122, v0
	v_mov_b32_e32 v123, v0
	v_mov_b32_e32 v124, v0
	v_mov_b32_e32 v125, v0
	v_mov_b32_e32 v126, v0
	v_mov_b32_e32 v127, v0
	s_mov_b64 s[74:75], 0x80
	v_add_u32_e32 v234, 0x10000, v143
	v_add_u32_e32 v235, 0x14000, v143
	v_add_u32_e32 v236, 0x18000, v143
	v_add_u32_e32 v237, 0x1c000, v143
	s_cmpk_lt_u32 s47, 0x100
	s_cbranch_scc0 .Lmy_pr_0
	s_setprio 1

.LBB0_1382:
	s_ashr_i32 s9, s8, 31
	s_lshl_b64 s[10:11], s[8:9], 20
	s_add_u32 s10, s66, s10
	s_addc_u32 s11, s67, s11
	s_and_b64 s[12:13], s[0:1], exec
	s_cselect_b32 s9, s11, s15
	s_cselect_b32 s33, s10, s14
	s_ashr_i32 s7, s6, 31
	s_lshl_b64 s[12:13], s[6:7], 20
	s_add_u32 s12, s60, s12
	s_addc_u32 s13, s61, s13
	s_and_b64 s[18:19], s[0:1], exec
	s_cselect_b32 s7, s13, s17
	s_cselect_b32 s34, s12, s16
	s_add_u32 s35, s16, 0x100
	v_mov_b32_e32 v0, 0
	s_addc_u32 s36, s17, 0
	s_mov_b32 s37, -2
	v_mov_b32_e32 v1, v0
	v_mov_b32_e32 v2, v0
	v_mov_b32_e32 v3, v0
	v_mov_b32_e32 v4, v0
	v_mov_b32_e32 v5, v0
	v_mov_b32_e32 v6, v0
	v_mov_b32_e32 v7, v0
	v_mov_b32_e32 v16, v0
	v_mov_b32_e32 v17, v0
	v_mov_b32_e32 v18, v0
	v_mov_b32_e32 v19, v0
	v_mov_b32_e32 v20, v0
	v_mov_b32_e32 v21, v0
	v_mov_b32_e32 v22, v0
	v_mov_b32_e32 v23, v0
	v_mov_b32_e32 v32, v0
	v_mov_b32_e32 v33, v0
	v_mov_b32_e32 v34, v0
	v_mov_b32_e32 v35, v0
	v_mov_b32_e32 v36, v0
	v_mov_b32_e32 v37, v0
	v_mov_b32_e32 v38, v0
	v_mov_b32_e32 v39, v0
	v_mov_b32_e32 v48, v0
	v_mov_b32_e32 v49, v0
	v_mov_b32_e32 v50, v0
	v_mov_b32_e32 v51, v0
	v_mov_b32_e32 v52, v0
	v_mov_b32_e32 v53, v0
	v_mov_b32_e32 v54, v0
	v_mov_b32_e32 v55, v0
	v_mov_b32_e32 v8, v0
	v_mov_b32_e32 v9, v0
	v_mov_b32_e32 v10, v0
	v_mov_b32_e32 v11, v0
	v_mov_b32_e32 v12, v0
	v_mov_b32_e32 v13, v0
	v_mov_b32_e32 v14, v0
	v_mov_b32_e32 v15, v0
	v_mov_b32_e32 v24, v0
	v_mov_b32_e32 v25, v0
	v_mov_b32_e32 v26, v0
	v_mov_b32_e32 v27, v0
	v_mov_b32_e32 v28, v0
	v_mov_b32_e32 v29, v0
	v_mov_b32_e32 v30, v0
	v_mov_b32_e32 v31, v0
	v_mov_b32_e32 v40, v0
	v_mov_b32_e32 v41, v0
	v_mov_b32_e32 v42, v0
	v_mov_b32_e32 v43, v0
	v_mov_b32_e32 v44, v0
	v_mov_b32_e32 v45, v0
	v_mov_b32_e32 v46, v0
	v_mov_b32_e32 v47, v0
	v_mov_b32_e32 v56, v0
	v_mov_b32_e32 v57, v0
	v_mov_b32_e32 v58, v0
	v_mov_b32_e32 v59, v0
	v_mov_b32_e32 v60, v0
	v_mov_b32_e32 v61, v0
	v_mov_b32_e32 v62, v0
	v_mov_b32_e32 v63, v0
	v_mov_b32_e32 v64, v0
	v_mov_b32_e32 v65, v0
	v_mov_b32_e32 v66, v0
	v_mov_b32_e32 v67, v0
	v_mov_b32_e32 v68, v0
	v_mov_b32_e32 v69, v0
	v_mov_b32_e32 v70, v0
	v_mov_b32_e32 v71, v0
	v_mov_b32_e32 v80, v0
	v_mov_b32_e32 v81, v0
	v_mov_b32_e32 v82, v0
	v_mov_b32_e32 v83, v0
	v_mov_b32_e32 v84, v0
	v_mov_b32_e32 v85, v0
	v_mov_b32_e32 v86, v0
	v_mov_b32_e32 v87, v0
	v_mov_b32_e32 v96, v0
	v_mov_b32_e32 v97, v0
	v_mov_b32_e32 v98, v0
	v_mov_b32_e32 v99, v0
	v_mov_b32_e32 v100, v0
	v_mov_b32_e32 v101, v0
	v_mov_b32_e32 v102, v0
	v_mov_b32_e32 v103, v0
	v_mov_b32_e32 v112, v0
	v_mov_b32_e32 v113, v0
	v_mov_b32_e32 v114, v0
	v_mov_b32_e32 v115, v0
	v_mov_b32_e32 v116, v0
	v_mov_b32_e32 v117, v0
	v_mov_b32_e32 v118, v0
	v_mov_b32_e32 v119, v0
	v_mov_b32_e32 v72, v0
	v_mov_b32_e32 v73, v0
	v_mov_b32_e32 v74, v0
	v_mov_b32_e32 v75, v0
	v_mov_b32_e32 v76, v0
	v_mov_b32_e32 v77, v0
	v_mov_b32_e32 v78, v0
	v_mov_b32_e32 v79, v0
	v_mov_b32_e32 v88, v0
	v_mov_b32_e32 v89, v0
	v_mov_b32_e32 v90, v0
	v_mov_b32_e32 v91, v0
	v_mov_b32_e32 v92, v0
	v_mov_b32_e32 v93, v0
	v_mov_b32_e32 v94, v0
	v_mov_b32_e32 v95, v0
	v_mov_b32_e32 v104, v0
	v_mov_b32_e32 v105, v0
	v_mov_b32_e32 v106, v0
	v_mov_b32_e32 v107, v0
	v_mov_b32_e32 v108, v0
	v_mov_b32_e32 v109, v0
	v_mov_b32_e32 v110, v0
	v_mov_b32_e32 v111, v0
	v_mov_b32_e32 v120, v0
	v_mov_b32_e32 v121, v0
	v_mov_b32_e32 v122, v0
	v_mov_b32_e32 v123, v0
	v_mov_b32_e32 v124, v0
	v_mov_b32_e32 v125, v0
	v_mov_b32_e32 v126, v0
	v_mov_b32_e32 v127, v0
	s_mov_b64 s[74:75], 0x80
	s_waitcnt vmcnt(0)
	v_add_u32_e32 v234, 0x10000, v141
	v_add_u32_e32 v235, 0x14000, v141
	v_add_u32_e32 v236, 0x18000, v141
	v_add_u32_e32 v237, 0x1c000, v141
	s_cmpk_lt_u32 s47, 0x100
	s_cbranch_scc0 .Lmy_pr_1
	s_setprio 1

.LBB0_1509:
	s_ashr_i32 s9, s8, 31
	s_lshl_b64 s[10:11], s[8:9], 20
	s_add_u32 s10, s66, s10
	s_addc_u32 s11, s67, s11
	s_and_b64 s[12:13], s[0:1], exec
	s_cselect_b32 s9, s11, s15
	s_cselect_b32 s30, s10, s14
	s_ashr_i32 s7, s6, 31
	s_lshl_b64 s[12:13], s[6:7], 20
	s_add_u32 s12, s62, s12
	s_addc_u32 s13, s63, s13
	s_and_b64 s[18:19], s[0:1], exec
	s_cselect_b32 s7, s13, s17
	s_cselect_b32 s31, s12, s16
	s_add_u32 s33, s16, 0x100
	s_addc_u32 s34, s17, 0
	s_add_u32 s14, s14, 0x80080
	v_mov_b32_e32 v0, 0
	s_addc_u32 s15, s15, 0
	s_mov_b32 s35, -2
	v_mov_b32_e32 v1, v0
	v_mov_b32_e32 v2, v0
	v_mov_b32_e32 v3, v0
	v_mov_b32_e32 v8, v0
	v_mov_b32_e32 v9, v0
	v_mov_b32_e32 v10, v0
	v_mov_b32_e32 v11, v0
	v_mov_b32_e32 v16, v0
	v_mov_b32_e32 v17, v0
	v_mov_b32_e32 v18, v0
	v_mov_b32_e32 v19, v0
	v_mov_b32_e32 v24, v0
	v_mov_b32_e32 v25, v0
	v_mov_b32_e32 v26, v0
	v_mov_b32_e32 v27, v0
	v_mov_b32_e32 v32, v0
	v_mov_b32_e32 v33, v0
	v_mov_b32_e32 v34, v0
	v_mov_b32_e32 v35, v0
	v_mov_b32_e32 v40, v0
	v_mov_b32_e32 v41, v0
	v_mov_b32_e32 v42, v0
	v_mov_b32_e32 v43, v0
	v_mov_b32_e32 v48, v0
	v_mov_b32_e32 v49, v0
	v_mov_b32_e32 v50, v0
	v_mov_b32_e32 v51, v0
	v_mov_b32_e32 v56, v0
	v_mov_b32_e32 v57, v0
	v_mov_b32_e32 v58, v0
	v_mov_b32_e32 v59, v0
	v_mov_b32_e32 v4, v0
	v_mov_b32_e32 v5, v0
	v_mov_b32_e32 v6, v0
	v_mov_b32_e32 v7, v0
	v_mov_b32_e32 v12, v0
	v_mov_b32_e32 v13, v0
	v_mov_b32_e32 v14, v0
	v_mov_b32_e32 v15, v0
	v_mov_b32_e32 v20, v0
	v_mov_b32_e32 v21, v0
	v_mov_b32_e32 v22, v0
	v_mov_b32_e32 v23, v0
	v_mov_b32_e32 v28, v0
	v_mov_b32_e32 v29, v0
	v_mov_b32_e32 v30, v0
	v_mov_b32_e32 v31, v0
	v_mov_b32_e32 v36, v0
	v_mov_b32_e32 v37, v0
	v_mov_b32_e32 v38, v0
	v_mov_b32_e32 v39, v0
	v_mov_b32_e32 v44, v0
	v_mov_b32_e32 v45, v0
	v_mov_b32_e32 v46, v0
	v_mov_b32_e32 v47, v0
	v_mov_b32_e32 v52, v0
	v_mov_b32_e32 v53, v0
	v_mov_b32_e32 v54, v0
	v_mov_b32_e32 v55, v0
	v_mov_b32_e32 v60, v0
	v_mov_b32_e32 v61, v0
	v_mov_b32_e32 v62, v0
	v_mov_b32_e32 v63, v0
	v_mov_b32_e32 v64, v0
	v_mov_b32_e32 v65, v0
	v_mov_b32_e32 v66, v0
	v_mov_b32_e32 v67, v0
	v_mov_b32_e32 v72, v0
	v_mov_b32_e32 v73, v0
	v_mov_b32_e32 v74, v0
	v_mov_b32_e32 v75, v0
	v_mov_b32_e32 v80, v0
	v_mov_b32_e32 v81, v0
	v_mov_b32_e32 v82, v0
	v_mov_b32_e32 v83, v0
	v_mov_b32_e32 v88, v0
	v_mov_b32_e32 v89, v0
	v_mov_b32_e32 v90, v0
	v_mov_b32_e32 v91, v0
	v_mov_b32_e32 v96, v0
	v_mov_b32_e32 v97, v0
	v_mov_b32_e32 v98, v0
	v_mov_b32_e32 v99, v0
	v_mov_b32_e32 v104, v0
	v_mov_b32_e32 v105, v0
	v_mov_b32_e32 v106, v0
	v_mov_b32_e32 v107, v0
	v_mov_b32_e32 v112, v0
	v_mov_b32_e32 v113, v0
	v_mov_b32_e32 v114, v0
	v_mov_b32_e32 v115, v0
	v_mov_b32_e32 v120, v0
	v_mov_b32_e32 v121, v0
	v_mov_b32_e32 v122, v0
	v_mov_b32_e32 v123, v0
	v_mov_b32_e32 v68, v0
	v_mov_b32_e32 v69, v0
	v_mov_b32_e32 v70, v0
	v_mov_b32_e32 v71, v0
	v_mov_b32_e32 v76, v0
	v_mov_b32_e32 v77, v0
	v_mov_b32_e32 v78, v0
	v_mov_b32_e32 v79, v0
	v_mov_b32_e32 v84, v0
	v_mov_b32_e32 v85, v0
	v_mov_b32_e32 v86, v0
	v_mov_b32_e32 v87, v0
	v_mov_b32_e32 v92, v0
	v_mov_b32_e32 v93, v0
	v_mov_b32_e32 v94, v0
	v_mov_b32_e32 v95, v0
	v_mov_b32_e32 v100, v0
	v_mov_b32_e32 v101, v0
	v_mov_b32_e32 v102, v0
	v_mov_b32_e32 v103, v0
	v_mov_b32_e32 v108, v0
	v_mov_b32_e32 v109, v0
	v_mov_b32_e32 v110, v0
	v_mov_b32_e32 v111, v0
	v_mov_b32_e32 v116, v0
	v_mov_b32_e32 v117, v0
	v_mov_b32_e32 v118, v0
	v_mov_b32_e32 v119, v0
	v_mov_b32_e32 v124, v0
	v_mov_b32_e32 v125, v0
	v_mov_b32_e32 v126, v0
	v_mov_b32_e32 v127, v0
	s_mov_b64 s[74:75], 0x80
	v_add_u32_e32 v234, 0x10000, v141
	v_add_u32_e32 v235, 0x14000, v141
	v_add_u32_e32 v236, 0x18000, v141
	v_add_u32_e32 v237, 0x1c000, v141
	s_cmpk_lt_u32 s47, 0x100
	s_cbranch_scc0 .Lmy_pr_2
	s_setprio 1

.LBB0_1589:
	s_add_u32 s30, s12, 0x100
	v_mov_b32_e32 v0, 0
	s_addc_u32 s31, s13, 0
	s_mov_b32 s33, -2
	v_mov_b32_e32 v1, v0
	v_mov_b32_e32 v2, v0
	v_mov_b32_e32 v3, v0
	v_mov_b32_e32 v4, v0
	v_mov_b32_e32 v5, v0
	v_mov_b32_e32 v6, v0
	v_mov_b32_e32 v7, v0
	v_mov_b32_e32 v16, v0
	v_mov_b32_e32 v17, v0
	v_mov_b32_e32 v18, v0
	v_mov_b32_e32 v19, v0
	v_mov_b32_e32 v20, v0
	v_mov_b32_e32 v21, v0
	v_mov_b32_e32 v22, v0
	v_mov_b32_e32 v23, v0
	v_mov_b32_e32 v32, v0
	v_mov_b32_e32 v33, v0
	v_mov_b32_e32 v34, v0
	v_mov_b32_e32 v35, v0
	v_mov_b32_e32 v36, v0
	v_mov_b32_e32 v37, v0
	v_mov_b32_e32 v38, v0
	v_mov_b32_e32 v39, v0
	v_mov_b32_e32 v48, v0
	v_mov_b32_e32 v49, v0
	v_mov_b32_e32 v50, v0
	v_mov_b32_e32 v51, v0
	v_mov_b32_e32 v52, v0
	v_mov_b32_e32 v53, v0
	v_mov_b32_e32 v54, v0
	v_mov_b32_e32 v55, v0
	v_mov_b32_e32 v8, v0
	v_mov_b32_e32 v9, v0
	v_mov_b32_e32 v10, v0
	v_mov_b32_e32 v11, v0
	v_mov_b32_e32 v12, v0
	v_mov_b32_e32 v13, v0
	v_mov_b32_e32 v14, v0
	v_mov_b32_e32 v15, v0
	v_mov_b32_e32 v24, v0
	v_mov_b32_e32 v25, v0
	v_mov_b32_e32 v26, v0
	v_mov_b32_e32 v27, v0
	v_mov_b32_e32 v28, v0
	v_mov_b32_e32 v29, v0
	v_mov_b32_e32 v30, v0
	v_mov_b32_e32 v31, v0
	v_mov_b32_e32 v40, v0
	v_mov_b32_e32 v41, v0
	v_mov_b32_e32 v42, v0
	v_mov_b32_e32 v43, v0
	v_mov_b32_e32 v44, v0
	v_mov_b32_e32 v45, v0
	v_mov_b32_e32 v46, v0
	v_mov_b32_e32 v47, v0
	v_mov_b32_e32 v56, v0
	v_mov_b32_e32 v57, v0
	v_mov_b32_e32 v58, v0
	v_mov_b32_e32 v59, v0
	v_mov_b32_e32 v60, v0
	v_mov_b32_e32 v61, v0
	v_mov_b32_e32 v62, v0
	v_mov_b32_e32 v63, v0
	v_mov_b32_e32 v64, v0
	v_mov_b32_e32 v65, v0
	v_mov_b32_e32 v66, v0
	v_mov_b32_e32 v67, v0
	v_mov_b32_e32 v68, v0
	v_mov_b32_e32 v69, v0
	v_mov_b32_e32 v70, v0
	v_mov_b32_e32 v71, v0
	v_mov_b32_e32 v80, v0
	v_mov_b32_e32 v81, v0
	v_mov_b32_e32 v82, v0
	v_mov_b32_e32 v83, v0
	v_mov_b32_e32 v84, v0
	v_mov_b32_e32 v85, v0
	v_mov_b32_e32 v86, v0
	v_mov_b32_e32 v87, v0
	v_mov_b32_e32 v96, v0
	v_mov_b32_e32 v97, v0
	v_mov_b32_e32 v98, v0
	v_mov_b32_e32 v99, v0
	v_mov_b32_e32 v100, v0
	v_mov_b32_e32 v101, v0
	v_mov_b32_e32 v102, v0
	v_mov_b32_e32 v103, v0
	v_mov_b32_e32 v112, v0
	v_mov_b32_e32 v113, v0
	v_mov_b32_e32 v114, v0
	v_mov_b32_e32 v115, v0
	v_mov_b32_e32 v116, v0
	v_mov_b32_e32 v117, v0
	v_mov_b32_e32 v118, v0
	v_mov_b32_e32 v119, v0
	v_mov_b32_e32 v72, v0
	v_mov_b32_e32 v73, v0
	v_mov_b32_e32 v74, v0
	v_mov_b32_e32 v75, v0
	v_mov_b32_e32 v76, v0
	v_mov_b32_e32 v77, v0
	v_mov_b32_e32 v78, v0
	v_mov_b32_e32 v79, v0
	v_mov_b32_e32 v88, v0
	v_mov_b32_e32 v89, v0
	v_mov_b32_e32 v90, v0
	v_mov_b32_e32 v91, v0
	v_mov_b32_e32 v92, v0
	v_mov_b32_e32 v93, v0
	v_mov_b32_e32 v94, v0
	v_mov_b32_e32 v95, v0
	v_mov_b32_e32 v104, v0
	v_mov_b32_e32 v105, v0
	v_mov_b32_e32 v106, v0
	v_mov_b32_e32 v107, v0
	v_mov_b32_e32 v108, v0
	v_mov_b32_e32 v109, v0
	v_mov_b32_e32 v110, v0
	v_mov_b32_e32 v111, v0
	v_mov_b32_e32 v120, v0
	v_mov_b32_e32 v121, v0
	v_mov_b32_e32 v122, v0
	v_mov_b32_e32 v123, v0
	v_mov_b32_e32 v124, v0
	v_mov_b32_e32 v125, v0
	v_mov_b32_e32 v126, v0
	v_mov_b32_e32 v127, v0
	s_mov_b64 s[36:37], 0x80
	s_waitcnt vmcnt(0)
	v_add_u32_e32 v234, 0x10000, v141
	v_add_u32_e32 v235, 0x14000, v141
	v_add_u32_e32 v236, 0x18000, v141
	v_add_u32_e32 v237, 0x1c000, v141
	s_cmpk_lt_u32 s47, 0x100
	s_cbranch_scc0 .Lmy_pr_3
	s_setprio 1
